# ret_scan: 17 KV loads issued together + counted waits, ST stores after the dependent chain (was load-wait-store per step)
# speedup vs baseline: 1.0194x; 1.0079x over previous
.LBB0_225:
	v_bfe_u32 v6, v0, 12, 1
	v_bfe_u32 v2, v0, 13, 2
	v_lshlrev_b32_e32 v1, 2, v6
	v_or3_b32 v4, v1, s20, v2
	v_ashrrev_i32_e32 v5, 31, v4
	v_lshl_add_u64 v[4:5], v[4:5], 2, s[40:41]
	global_load_dword v1, v[4:5], off
	v_ashrrev_i32_e32 v3, 15, v0
	s_mov_b32 s23, 0x3ffff
	s_waitcnt vmcnt(0)
	v_mul_f32_e32 v4, 0xbfb8aa3b, v1
	v_fma_f32 v5, v1, s70, -v4
	v_rndne_f32_e32 v7, v4
	v_fmac_f32_e32 v5, 0xb2a5705f, v1
	v_sub_f32_e32 v4, v4, v7
	v_add_f32_e32 v4, v4, v5
	v_exp_f32_e32 v4, v4
	v_cvt_i32_f32_e32 v5, v7
	v_cmp_nlt_f32_e32 vcc, s71, v1
	v_ldexp_f32 v4, v4, v5
	s_nop 0
	v_cndmask_b32_e32 v4, 0, v4, vcc
	v_cmp_ngt_f32_e32 vcc, s3, v1
	s_nop 1
	v_cndmask_b32_e32 v1, v238, v4, vcc
	v_add_f32_e32 v7, 1.0, v1
	v_add_f32_e32 v4, -1.0, v7
	v_sub_f32_e32 v5, v4, v7
	v_add_f32_e32 v5, 1.0, v5
	v_sub_f32_e32 v4, v1, v4
	v_add_f32_e32 v8, v4, v5
	v_frexp_mant_f32_e32 v4, v7
	v_cmp_gt_f32_e32 vcc, s4, v4
	v_cvt_f64_f32_e32 v[4:5], v7
	v_frexp_exp_i32_f64_e32 v4, v[4:5]
	v_subbrev_co_u32_e32 v4, vcc, 0, v4, vcc
	v_sub_u32_e32 v5, 0, v4
	v_ldexp_f32 v7, v7, v5
	v_ldexp_f32 v5, v8, v5
	v_add_f32_e32 v8, -1.0, v7
	v_add_f32_e32 v9, 1.0, v8
	v_sub_f32_e32 v9, v7, v9
	v_add_f32_e32 v9, v5, v9
	v_add_f32_e32 v10, v8, v9
	v_sub_f32_e32 v8, v8, v10
	v_add_f32_e32 v8, v9, v8
	v_add_f32_e32 v9, 1.0, v7
	v_add_f32_e32 v11, -1.0, v9
	v_sub_f32_e32 v7, v7, v11
	v_add_f32_e32 v5, v5, v7
	v_add_f32_e32 v7, v9, v5
	v_sub_f32_e32 v9, v9, v7
	v_add_f32_e32 v5, v5, v9
	v_rcp_f32_e32 v9, v7
	v_cvt_f32_i32_e32 v4, v4
	v_cmp_neq_f32_e32 vcc, s21, v1
	v_mul_f32_e32 v11, v10, v9
	v_mul_f32_e32 v12, v7, v11
	v_fma_f32 v13, v11, v7, -v12
	v_fmac_f32_e32 v13, v11, v5
	v_add_f32_e32 v14, v12, v13
	v_sub_f32_e32 v15, v10, v14
	v_sub_f32_e32 v10, v10, v15
	v_sub_f32_e32 v12, v14, v12
	v_sub_f32_e32 v10, v10, v14
	v_add_f32_e32 v8, v8, v10
	v_sub_f32_e32 v10, v12, v13
	v_add_f32_e32 v8, v10, v8
	v_add_f32_e32 v10, v15, v8
	v_mul_f32_e32 v12, v9, v10
	v_mul_f32_e32 v13, v7, v12
	v_fma_f32 v7, v12, v7, -v13
	v_fmac_f32_e32 v7, v12, v5
	v_sub_f32_e32 v5, v15, v10
	v_add_f32_e32 v5, v8, v5
	v_add_f32_e32 v8, v13, v7
	v_sub_f32_e32 v14, v10, v8
	v_sub_f32_e32 v10, v10, v14
	v_sub_f32_e32 v13, v8, v13
	v_sub_f32_e32 v8, v10, v8
	v_add_f32_e32 v5, v5, v8
	v_sub_f32_e32 v7, v13, v7
	v_add_f32_e32 v5, v7, v5
	v_add_f32_e32 v7, v11, v12
	v_add_f32_e32 v5, v14, v5
	v_sub_f32_e32 v8, v7, v11
	v_mul_f32_e32 v5, v9, v5
	v_sub_f32_e32 v8, v12, v8
	v_add_f32_e32 v5, v8, v5
	v_mul_f32_e32 v11, 0x3f317218, v4
	v_add_f32_e32 v8, v7, v5
	v_fma_f32 v12, v4, s5, -v11
	v_mul_f32_e32 v9, v8, v8
	v_fmac_f32_e32 v12, 0xb102e308, v4
	v_sub_f32_e32 v4, v8, v7
	v_fmamk_f32 v10, v9, 0x3e9b6dac, v222
	v_sub_f32_e32 v4, v5, v4
	v_add_f32_e32 v5, v11, v12
	v_fmaak_f32 v10, v9, v10, 0x3f2aaada
	v_sub_f32_e32 v7, v5, v11
	v_ldexp_f32 v11, v8, 1
	v_mul_f32_e32 v8, v8, v9
	v_mul_f32_e32 v8, v8, v10
	v_add_f32_e32 v9, v11, v8
	v_sub_f32_e32 v10, v9, v11
	v_ldexp_f32 v4, v4, 1
	v_sub_f32_e32 v8, v8, v10
	v_add_f32_e32 v4, v4, v8
	v_add_f32_e32 v8, v9, v4
	v_sub_f32_e32 v9, v8, v9
	v_sub_f32_e32 v4, v4, v9
	v_add_f32_e32 v9, v5, v8
	v_sub_f32_e32 v10, v9, v5
	v_sub_f32_e32 v11, v9, v10
	v_sub_f32_e32 v7, v12, v7
	v_sub_f32_e32 v5, v5, v11
	v_sub_f32_e32 v8, v8, v10
	v_add_f32_e32 v5, v8, v5
	v_add_f32_e32 v8, v7, v4
	v_sub_f32_e32 v10, v8, v7
	v_sub_f32_e32 v11, v8, v10
	v_sub_f32_e32 v7, v7, v11
	v_sub_f32_e32 v4, v4, v10
	v_add_f32_e32 v5, v8, v5
	v_add_f32_e32 v4, v4, v7
	v_add_f32_e32 v7, v9, v5
	v_sub_f32_e32 v8, v7, v9
	v_sub_f32_e32 v5, v5, v8
	v_add_f32_e32 v4, v4, v5
	v_add_f32_e32 v4, v7, v4
	v_cndmask_b32_e32 v4, v238, v4, vcc
	v_cmp_lt_f32_e64 vcc, |v1|, s6
	v_lshlrev_b32_e32 v9, 6, v3
	v_and_b32_e32 v8, 0x1fff, v0
	v_cndmask_b32_e32 v1, v4, v1, vcc
	v_mul_f32_e32 v1, 0xc3000000, v1
	v_mul_f32_e32 v4, 0x3fb8aa3b, v1
	v_fma_f32 v5, v1, s7, -v4
	v_rndne_f32_e32 v7, v4
	v_fmac_f32_e32 v5, 0x32a5705f, v1
	v_sub_f32_e32 v4, v4, v7
	v_add_f32_e32 v4, v4, v5
	v_exp_f32_e32 v4, v4
	v_cvt_i32_f32_e32 v5, v7
	v_cmp_ngt_f32_e32 vcc, s8, v1
	v_add_u32_e32 v0, s22, v0
	v_lshlrev_b32_e32 v184, 1, v8
	v_ldexp_f32 v4, v4, v5
	v_cndmask_b32_e32 v4, 0, v4, vcc
	v_cmp_nlt_f32_e32 vcc, s9, v1
	s_nop 1
	v_cndmask_b32_e32 v1, v238, v4, vcc
	v_cmp_eq_u32_e32 vcc, 0, v6
	v_lshlrev_b32_e32 v4, 1, v2
	v_lshl_or_b32 v3, v3, 3, v4
	v_add_u32_e32 v10, 0x200, v3
	v_add_u32_e32 v3, 0x201, v3
	v_lshl_or_b32 v7, v2, 4, v9
	v_lshlrev_b32_e32 v26, 2, v8
	v_cndmask_b32_e32 v30, v3, v10, vcc
	v_cndmask_b32_e32 v31, v10, v3, vcc
	v_or_b32_e32 v5, 15, v7
	v_cndmask_b32_e32 v32, v5, v7, vcc
	v_or_b32_e32 v4, 1, v7
	v_or_b32_e32 v5, 14, v7
	v_cndmask_b32_e32 v33, v5, v4, vcc
	v_or_b32_e32 v4, 2, v7
	v_or_b32_e32 v5, 13, v7
	v_cndmask_b32_e32 v34, v5, v4, vcc
	v_or_b32_e32 v4, 3, v7
	v_or_b32_e32 v5, 12, v7
	v_cndmask_b32_e32 v35, v5, v4, vcc
	v_or_b32_e32 v4, 4, v7
	v_or_b32_e32 v5, 11, v7
	v_cndmask_b32_e32 v36, v5, v4, vcc
	v_or_b32_e32 v4, 5, v7
	v_or_b32_e32 v5, 10, v7
	v_cndmask_b32_e32 v37, v5, v4, vcc
	v_or_b32_e32 v4, 6, v7
	v_or_b32_e32 v5, 9, v7
	v_cndmask_b32_e32 v38, v5, v4, vcc
	v_or_b32_e32 v4, 7, v7
	v_or_b32_e32 v5, 8, v7
	v_cndmask_b32_e32 v39, v5, v4, vcc
	v_or_b32_e32 v4, 8, v7
	v_or_b32_e32 v5, 7, v7
	v_cndmask_b32_e32 v40, v5, v4, vcc
	v_or_b32_e32 v4, 9, v7
	v_or_b32_e32 v5, 6, v7
	v_cndmask_b32_e32 v41, v5, v4, vcc
	v_or_b32_e32 v4, 10, v7
	v_or_b32_e32 v5, 5, v7
	v_cndmask_b32_e32 v42, v5, v4, vcc
	v_or_b32_e32 v4, 11, v7
	v_or_b32_e32 v5, 4, v7
	v_cndmask_b32_e32 v43, v5, v4, vcc
	v_or_b32_e32 v4, 12, v7
	v_or_b32_e32 v5, 3, v7
	v_cndmask_b32_e32 v44, v5, v4, vcc
	v_or_b32_e32 v4, 13, v7
	v_or_b32_e32 v5, 2, v7
	v_cndmask_b32_e32 v45, v5, v4, vcc
	v_or_b32_e32 v4, 14, v7
	v_or_b32_e32 v5, 1, v7
	v_cndmask_b32_e32 v46, v5, v4, vcc
	v_or_b32_e32 v4, 15, v7
	v_cndmask_b32_e32 v47, v7, v4, vcc
	v_lshl_or_b32 v30, v30, 15, v26
	v_lshl_or_b32 v31, v31, 15, v26
	v_lshl_or_b32 v32, v32, 15, v26
	v_lshl_or_b32 v33, v33, 15, v26
	v_lshl_or_b32 v34, v34, 15, v26
	v_lshl_or_b32 v35, v35, 15, v26
	v_lshl_or_b32 v36, v36, 15, v26
	v_lshl_or_b32 v37, v37, 15, v26
	v_lshl_or_b32 v38, v38, 15, v26
	v_lshl_or_b32 v39, v39, 15, v26
	v_lshl_or_b32 v40, v40, 15, v26
	v_lshl_or_b32 v41, v41, 15, v26
	v_lshl_or_b32 v42, v42, 15, v26
	v_lshl_or_b32 v43, v43, 15, v26
	v_lshl_or_b32 v44, v44, 15, v26
	v_lshl_or_b32 v45, v45, 15, v26
	v_lshl_or_b32 v46, v46, 15, v26
	v_lshl_or_b32 v47, v47, 15, v26
	global_load_dword v50, v30, s[62:63]
	global_load_dword v51, v31, s[62:63]
	global_load_dword v52, v32, s[62:63]
	global_load_dword v53, v33, s[62:63]
	global_load_dword v54, v34, s[62:63]
	global_load_dword v55, v35, s[62:63]
	global_load_dword v56, v36, s[62:63]
	global_load_dword v57, v37, s[62:63]
	global_load_dword v58, v38, s[62:63]
	global_load_dword v59, v39, s[62:63]
	global_load_dword v60, v40, s[62:63]
	global_load_dword v61, v41, s[62:63]
	global_load_dword v62, v42, s[62:63]
	global_load_dword v63, v43, s[62:63]
	global_load_dword v64, v44, s[62:63]
	global_load_dword v65, v45, s[62:63]
	global_load_dword v66, v46, s[62:63]
	v_lshrrev_b32_e32 v30, 1, v30
	v_lshrrev_b32_e32 v31, 1, v31
	v_lshrrev_b32_e32 v32, 1, v32
	v_lshrrev_b32_e32 v33, 1, v33
	v_lshrrev_b32_e32 v34, 1, v34
	v_lshrrev_b32_e32 v35, 1, v35
	v_lshrrev_b32_e32 v36, 1, v36
	v_lshrrev_b32_e32 v37, 1, v37
	v_lshrrev_b32_e32 v38, 1, v38
	v_lshrrev_b32_e32 v39, 1, v39
	v_lshrrev_b32_e32 v40, 1, v40
	v_lshrrev_b32_e32 v41, 1, v41
	v_lshrrev_b32_e32 v42, 1, v42
	v_lshrrev_b32_e32 v43, 1, v43
	v_lshrrev_b32_e32 v44, 1, v44
	v_lshrrev_b32_e32 v45, 1, v45
	v_lshrrev_b32_e32 v46, 1, v46
	v_lshrrev_b32_e32 v47, 1, v47
	s_waitcnt vmcnt(16)
	v_fmac_f32_e32 v50, 0, v1
	v_bfe_u32 v4, v50, 16, 1
	v_add3_u32 v70, v50, v4, s97
	s_waitcnt vmcnt(15)
	v_fmac_f32_e32 v51, v1, v50
	v_bfe_u32 v4, v51, 16, 1
	v_add3_u32 v71, v51, v4, s97
	s_waitcnt vmcnt(14)
	v_fmac_f32_e32 v52, v1, v51
	v_bfe_u32 v4, v52, 16, 1
	v_add3_u32 v72, v52, v4, s97
	s_waitcnt vmcnt(13)
	v_fmac_f32_e32 v53, v1, v52
	v_bfe_u32 v4, v53, 16, 1
	v_add3_u32 v73, v53, v4, s97
	s_waitcnt vmcnt(12)
	v_fmac_f32_e32 v54, v1, v53
	v_bfe_u32 v4, v54, 16, 1
	v_add3_u32 v74, v54, v4, s97
	s_waitcnt vmcnt(11)
	v_fmac_f32_e32 v55, v1, v54
	v_bfe_u32 v4, v55, 16, 1
	v_add3_u32 v75, v55, v4, s97
	s_waitcnt vmcnt(10)
	v_fmac_f32_e32 v56, v1, v55
	v_bfe_u32 v4, v56, 16, 1
	v_add3_u32 v76, v56, v4, s97
	s_waitcnt vmcnt(9)
	v_fmac_f32_e32 v57, v1, v56
	v_bfe_u32 v4, v57, 16, 1
	v_add3_u32 v77, v57, v4, s97
	s_waitcnt vmcnt(8)
	v_fmac_f32_e32 v58, v1, v57
	v_bfe_u32 v4, v58, 16, 1
	v_add3_u32 v78, v58, v4, s97
	s_waitcnt vmcnt(7)
	v_fmac_f32_e32 v59, v1, v58
	v_bfe_u32 v4, v59, 16, 1
	v_add3_u32 v79, v59, v4, s97
	s_waitcnt vmcnt(6)
	v_fmac_f32_e32 v60, v1, v59
	v_bfe_u32 v4, v60, 16, 1
	v_add3_u32 v80, v60, v4, s97
	s_waitcnt vmcnt(5)
	v_fmac_f32_e32 v61, v1, v60
	v_bfe_u32 v4, v61, 16, 1
	v_add3_u32 v81, v61, v4, s97
	s_waitcnt vmcnt(4)
	v_fmac_f32_e32 v62, v1, v61
	v_bfe_u32 v4, v62, 16, 1
	v_add3_u32 v82, v62, v4, s97
	s_waitcnt vmcnt(3)
	v_fmac_f32_e32 v63, v1, v62
	v_bfe_u32 v4, v63, 16, 1
	v_add3_u32 v83, v63, v4, s97
	s_waitcnt vmcnt(2)
	v_fmac_f32_e32 v64, v1, v63
	v_bfe_u32 v4, v64, 16, 1
	v_add3_u32 v84, v64, v4, s97
	s_waitcnt vmcnt(1)
	v_fmac_f32_e32 v65, v1, v64
	v_bfe_u32 v4, v65, 16, 1
	v_add3_u32 v85, v65, v4, s97
	s_waitcnt vmcnt(0)
	v_fmac_f32_e32 v66, v1, v65
	v_bfe_u32 v4, v66, 16, 1
	v_add3_u32 v86, v66, v4, s97
	global_store_short v30, v185, s[58:59]
	global_store_short_d16_hi v31, v70, s[58:59]
	global_store_short_d16_hi v32, v71, s[58:59]
	global_store_short_d16_hi v33, v72, s[58:59]
	global_store_short_d16_hi v34, v73, s[58:59]
	global_store_short_d16_hi v35, v74, s[58:59]
	global_store_short_d16_hi v36, v75, s[58:59]
	global_store_short_d16_hi v37, v76, s[58:59]
	global_store_short_d16_hi v38, v77, s[58:59]
	global_store_short_d16_hi v39, v78, s[58:59]
	global_store_short_d16_hi v40, v79, s[58:59]
	global_store_short_d16_hi v41, v80, s[58:59]
	global_store_short_d16_hi v42, v81, s[58:59]
	global_store_short_d16_hi v43, v82, s[58:59]
	global_store_short_d16_hi v44, v83, s[58:59]
	global_store_short_d16_hi v45, v84, s[58:59]
	global_store_short_d16_hi v46, v85, s[58:59]
	global_store_short_d16_hi v47, v86, s[58:59]
	v_cmp_lt_i32_e32 vcc, s23, v0
	s_or_b64 s[36:37], vcc, s[36:37]
	s_andn2_b64 exec, exec, s[36:37]
	s_cbranch_execnz .LBB0_225
